# v27 + softmax mask folded into score select as -inf (drops 12 NA + 17 SWA VALU ops per key block)
# speedup vs baseline: 1.0067x; 1.0067x over previous
.LBB0_241:
	s_or_b64 exec, exec, s[0:1]
	s_waitcnt lgkmcnt(0)
	v_mov_b32_e32 v0, v178
	s_barrier
	v_readlane_b32 s2, v254, 22
	v_ashrrev_i32_e32 v1, 6, v0
	s_mov_b64 s[16:17], 0
	s_mov_b64 s[0:1], 0
	v_add_u32_e32 v69, s2, v1
	s_lshl_b32 s84, s90, 3
	s_movk_i32 s2, 0x1000
	v_cmp_gt_i32_e32 vcc, s2, v69
	s_mov_b64 s[2:3], exec
	v_writelane_b32 v254, s2, 43
	s_mov_b32 s4, s88
	s_nop 0
	v_writelane_b32 v254, s3, 44
	v_writelane_b32 v254, s90, 45
	s_and_b64 s[2:3], s[2:3], vcc
	s_nop 0
	v_writelane_b32 v254, s91, 46
	v_writelane_b32 v254, s4, 47
	s_nop 1
	v_writelane_b32 v254, s5, 48
	s_mov_b64 exec, s[2:3]
	s_cbranch_execz .LBB0_250
	v_readlane_b32 s2, v254, 0
	v_readlane_b32 s3, v254, 1
	s_add_u32 s0, s2, s0
	s_addc_u32 s1, s3, s1
	s_add_u32 s18, s0, 0xc120000
	v_and_b32_e32 v90, 31, v0
	s_addc_u32 s19, s1, 0
	s_add_u32 s20, s0, 0x15d20000
	v_mov_b32_e32 v65, 0
	v_lshlrev_b32_e32 v64, 12, v90
	v_and_b32_e32 v4, 63, v0
	s_addc_u32 s21, s1, 0
	v_lshl_add_u64 v[2:3], s[0:1], 0, v[64:65]
	s_mov_b64 s[0:1], 0x14920000
	s_movk_i32 s2, 0x780
	v_lshl_add_u64 v[66:67], v[2:3], 0, s[0:1]
	v_or_b32_e32 v2, 0x180, v4
	s_movk_i32 s0, 0x191
	v_mul_lo_u32 v91, v1, s2
	v_cmp_gt_u32_e64 s[22:23], s0, v2
	v_readlane_b32 s0, v254, 6
	v_readlane_b32 s1, v254, 7
	v_readlane_b32 s2, v254, 8
	v_readlane_b32 s3, v254, 9
	v_readlane_b32 s4, v254, 10
	v_readlane_b32 s5, v254, 11
	v_readlane_b32 s6, v254, 12
	v_readlane_b32 s7, v254, 13
	v_readlane_b32 s8, v254, 14
	v_readlane_b32 s9, v254, 15
	v_readlane_b32 s10, v254, 16
	v_readlane_b32 s11, v254, 17
	v_readlane_b32 s12, v254, 18
	v_readlane_b32 s13, v254, 19
	v_readlane_b32 s14, v254, 20
	v_readlane_b32 s15, v254, 21
	v_writelane_b32 v254, s18, 49
	v_bfe_u32 v1, v0, 5, 1
	v_lshlrev_b32_e32 v68, 2, v1
	v_writelane_b32 v254, s19, 50
	v_writelane_b32 v254, s84, 51
	v_lshlrev_b32_e32 v64, 2, v4
	v_bfe_u32 v92, v0, 4, 1
	v_writelane_b32 v254, s85, 52
	v_writelane_b32 v254, s20, 53
	v_and_b32_e32 v93, 15, v0
	v_lshlrev_b32_e32 v0, 3, v1
	v_writelane_b32 v254, s21, 54
	v_add_u32_e32 v94, v91, v64
	v_lshl_add_u64 v[70:71], s[10:11], 0, v[64:65]
	v_lshlrev_b32_e32 v64, 4, v1
	v_lshlrev_b32_e32 v76, 1, v68
	v_writelane_b32 v254, s22, 55
	v_lshl_add_u64 v[72:73], s[18:19], 0, v[64:65]
	s_movk_i32 s89, 0x2200
	v_lshlrev_b32_e32 v74, 1, v0
	v_mov_b32_e32 v78, v76
	v_mov_b32_e32 v79, v65
	v_mov_b32_e32 v95, 0xff800000
	v_writelane_b32 v254, s23, 56
	s_branch .LBB0_244

.LBB0_248:
	v_add_u32_e32 v32, s33, v96
	v_lshl_or_b32 v64, v32, 6, v75
	v_sub_u32_e32 v33, v32, v77
	v_cmp_ge_u32_e32 vcc, v32, v98
	v_cmp_lt_u32_e64 s[68:69], v32, v100
	v_add_u32_e32 v32, v99, v64
	v_max_i32_e32 v33, -7, v33
	v_mad_i64_i32 v[36:37], s[2:3], v32, s89, v[86:87]
	v_add_u32_e32 v38, 7, v33
	global_load_dwordx4 v[32:35], v[36:37], off offset:1024
	global_load_dwordx4 v[118:121], v[36:37], off offset:1056
	global_load_dwordx4 v[122:125], v[36:37], off offset:1088
	global_load_dwordx4 v[126:129], v[36:37], off offset:1120
	s_and_b64 s[84:85], vcc, s[68:69]
	v_min_u32_e32 v36, 14, v38
	s_movk_i32 vcc_lo, 0x7c
	v_mad_u32_u24 v130, v36, vcc_lo, v91
	v_lshl_add_u32 v160, v161, 2, v130
	ds_read_b32 v131, v160
	ds_read_b32 v132, v160 offset:4
	v_readlane_b32 s2, v254, 61
	v_readlane_b32 s3, v254, 62
	s_and_b64 s[2:3], s[84:85], s[2:3]
	s_and_b64 s[96:97], s[84:85], s[6:7]
	s_and_b64 s[94:95], s[84:85], s[10:11]
	s_and_b64 s[92:93], s[84:85], s[14:15]
	s_and_b64 s[96:97], s[96:97], s[8:9]
	s_and_b64 s[2:3], s[2:3], s[4:5]
	s_and_b64 s[90:91], s[84:85], s[18:19]
	s_and_b64 s[88:89], s[84:85], s[22:23]
	s_and_b64 s[94:95], s[94:95], s[12:13]
	s_and_b64 s[92:93], s[92:93], s[16:17]
	s_and_b64 s[86:87], s[84:85], s[26:27]
	s_and_b64 s[68:69], s[84:85], s[30:31]
	s_and_b64 s[90:91], s[90:91], s[20:21]
	s_and_b64 s[88:89], s[88:89], s[24:25]
	s_and_b64 s[70:71], s[84:85], s[36:37]
	s_and_b64 s[72:73], s[84:85], s[40:41]
	s_and_b64 s[86:87], s[86:87], s[28:29]
	s_and_b64 s[68:69], s[68:69], s[34:35]
	s_and_b64 s[74:75], s[84:85], s[44:45]
	s_and_b64 s[76:77], s[84:85], s[48:49]
	s_and_b64 s[70:71], s[70:71], s[38:39]
	s_and_b64 s[72:73], s[72:73], s[42:43]
	s_and_b64 s[78:79], s[84:85], s[52:53]
	s_and_b64 s[80:81], s[84:85], s[56:57]
	s_and_b64 s[74:75], s[74:75], s[46:47]
	s_and_b64 s[76:77], s[76:77], s[50:51]
	s_and_b64 s[82:83], s[84:85], s[60:61]
	s_and_b64 s[84:85], s[84:85], s[64:65]
	s_and_b64 s[78:79], s[78:79], s[54:55]
	s_and_b64 s[80:81], s[80:81], s[58:59]
	s_and_b64 s[82:83], s[82:83], s[62:63]
	s_and_b64 s[84:85], s[84:85], s[66:67]
	s_add_i32 s33, s33, 1
	v_cmp_ge_i32_e32 vcc, s33, v97
	s_or_b64 s[0:1], vcc, s[0:1]
	s_waitcnt vmcnt(3)
	v_mfma_f32_32x32x16_bf16 v[32:47], v[32:35], v[48:51], 0
	s_waitcnt vmcnt(2)
	v_mfma_f32_32x32x16_bf16 v[32:47], v[118:121], v[52:55], v[32:47]
	ds_read_b32 v118, v160 offset:8
	ds_read_b32 v119, v160 offset:12
	ds_read_b32 v120, v160 offset:32
	ds_read_b32 v121, v160 offset:36
	ds_read_b32 v133, v160 offset:40
	ds_read_b32 v134, v160 offset:44
	ds_read_b32 v135, v160 offset:64
	s_waitcnt vmcnt(1)
	v_mfma_f32_32x32x16_bf16 v[32:47], v[122:125], v[56:59], v[32:47]
	ds_read_b32 v122, v160 offset:68
	ds_read_b32 v123, v160 offset:72
	ds_read_b32 v124, v160 offset:76
	ds_read_b32 v125, v160 offset:96
	ds_read_b32 v136, v160 offset:100
	ds_read_b32 v137, v160 offset:104
	ds_read_b32 v130, v160 offset:108
	s_waitcnt vmcnt(0)
	v_mfma_f32_32x32x16_bf16 v[32:47], v[126:129], v[60:63], v[32:47]
	s_waitcnt lgkmcnt(14)
	s_nop 10
	v_add_f32_e32 v32, v32, v131
	v_add_f32_e32 v33, v33, v132
	s_waitcnt lgkmcnt(13)
	v_add_f32_e32 v34, v34, v118
	s_waitcnt lgkmcnt(12)
	v_add_f32_e32 v118, v35, v119
	v_cndmask_b32_e64 v32, v95, v32, s[2:3]
	s_waitcnt lgkmcnt(11)
	v_add_f32_e32 v119, v36, v120
	v_cndmask_b32_e64 v33, v95, v33, s[96:97]
	v_max_f32_e32 v35, 0xf149f2ca, v32
	s_waitcnt lgkmcnt(10)
	v_add_f32_e32 v120, v37, v121
	s_waitcnt lgkmcnt(9)
	v_add_f32_e32 v121, v38, v133
	v_cndmask_b32_e64 v34, v95, v34, s[94:95]
	v_cndmask_b32_e64 v118, v95, v118, s[92:93]
	v_max_f32_e32 v35, v35, v33
	s_waitcnt lgkmcnt(8)
	v_add_f32_e32 v126, v39, v134
	s_waitcnt lgkmcnt(7)
	v_add_f32_e32 v127, v40, v135
	v_cndmask_b32_e64 v119, v95, v119, s[90:91]
	v_cndmask_b32_e64 v120, v95, v120, s[88:89]
	v_max3_f32 v35, v35, v34, v118
	s_waitcnt lgkmcnt(6)
	v_add_f32_e32 v122, v41, v122
	s_waitcnt lgkmcnt(5)
	v_add_f32_e32 v123, v42, v123
	v_cndmask_b32_e64 v121, v95, v121, s[86:87]
	v_cndmask_b32_e64 v126, v95, v126, s[68:69]
	v_max3_f32 v35, v35, v119, v120
	s_waitcnt lgkmcnt(4)
	v_add_f32_e32 v124, v43, v124
	s_waitcnt lgkmcnt(3)
	v_add_f32_e32 v125, v44, v125
	v_cndmask_b32_e64 v127, v95, v127, s[70:71]
	v_cndmask_b32_e64 v122, v95, v122, s[72:73]
	v_max3_f32 v35, v35, v121, v126
	s_waitcnt lgkmcnt(2)
	v_add_f32_e32 v128, v45, v136
	s_waitcnt lgkmcnt(1)
	v_add_f32_e32 v129, v46, v137
	v_cndmask_b32_e64 v123, v95, v123, s[74:75]
	v_cndmask_b32_e64 v124, v95, v124, s[76:77]
	v_max3_f32 v35, v35, v127, v122
	s_waitcnt lgkmcnt(0)
	v_add_f32_e32 v130, v47, v130
	v_cndmask_b32_e64 v125, v95, v125, s[78:79]
	v_cndmask_b32_e64 v128, v95, v128, s[80:81]
	v_max3_f32 v35, v35, v123, v124
	v_cndmask_b32_e64 v129, v95, v129, s[82:83]
	v_cndmask_b32_e64 v130, v95, v130, s[84:85]
	v_max3_f32 v35, v35, v125, v128
	v_max3_f32 v35, v35, v129, v130
	v_mov_b32_e32 v36, v35
	s_nop 1
	v_permlane32_swap_b32_e32 v35, v36
	v_max3_f32 v131, v83, v35, v36
	v_sub_f32_e32 v32, v32, v131
	v_mul_f32_e32 v32, 0x3fb8aa3b, v32
	v_exp_f32_e32 v132, v32
	v_mov_b32_e32 v135, v117
	v_sub_f32_e32 v117, v118, v131
	v_sub_f32_e32 v118, v119, v131
	v_sub_f32_e32 v32, v33, v131
	v_mul_f32_e32 v32, 0x3fb8aa3b, v32
	v_exp_f32_e32 v133, v32
	v_sub_f32_e32 v119, v120, v131
	v_sub_f32_e32 v120, v121, v131
	v_sub_f32_e32 v121, v126, v131
	v_sub_f32_e32 v32, v34, v131
	v_mul_f32_e32 v32, 0x3fb8aa3b, v32
	v_exp_f32_e32 v134, v32
	v_mul_f32_e32 v117, 0x3fb8aa3b, v117
	v_mul_f32_e32 v118, 0x3fb8aa3b, v118
	v_mul_f32_e32 v119, 0x3fb8aa3b, v119
	v_lshlrev_b64 v[32:33], 1, v[64:65]
	v_lshl_add_u64 v[38:39], v[88:89], 0, v[32:33]
	v_lshl_add_u64 v[38:39], v[38:39], 0, v[164:165]
	v_lshl_add_u64 v[36:37], v[84:85], 0, v[32:33]
	global_load_dwordx4 v[32:35], v[38:39], off
	v_lshl_add_u64 v[46:47], v[36:37], 0, v[78:79]
	v_lshl_add_u64 v[46:47], v[46:47], 0, v[164:165]
	global_load_dwordx4 v[36:39], v[38:39], off offset:32
	s_nop 0
	s_nop 0
	global_load_dwordx4 v[40:43], v[46:47], off
	global_load_dwordx4 v[44:47], v[46:47], off offset:32
	s_nop 0
	v_sub_f32_e32 v64, v83, v131
	v_mul_f32_e32 v120, 0x3fb8aa3b, v120
	v_mul_f32_e32 v121, 0x3fb8aa3b, v121
	v_mul_f32_e32 v64, 0x3fb8aa3b, v64
	v_exp_f32_e32 v117, v117
	v_exp_f32_e32 v118, v118
	v_exp_f32_e32 v119, v119
	v_exp_f32_e32 v120, v120
	v_exp_f32_e32 v121, v121
	v_exp_f32_e32 v64, v64
	v_sub_f32_e32 v126, v127, v131
	v_sub_f32_e32 v122, v122, v131
	v_sub_f32_e32 v123, v123, v131
	v_sub_f32_e32 v124, v124, v131
	v_sub_f32_e32 v125, v125, v131
	v_sub_f32_e32 v127, v128, v131
	v_sub_f32_e32 v128, v129, v131
	v_sub_f32_e32 v129, v130, v131
	v_mov_b32_e32 v83, v131
	v_cndmask_b32_e64 v130, 0, v118, s[90:91]
	v_cndmask_b32_e64 v131, 0, v119, s[88:89]
	v_cndmask_b32_e64 v136, 0, v120, s[86:87]
	v_cndmask_b32_e64 v137, 0, v121, s[68:69]
	v_pk_mul_f32 v[14:15], v[14:15], v[64:65] op_sel_hi:[1,0]
	v_pk_mul_f32 v[12:13], v[12:13], v[64:65] op_sel_hi:[1,0]
	v_pk_mul_f32 v[10:11], v[10:11], v[64:65] op_sel_hi:[1,0]
	v_pk_mul_f32 v[8:9], v[8:9], v[64:65] op_sel_hi:[1,0]
	v_pk_mul_f32 v[6:7], v[6:7], v[64:65] op_sel_hi:[1,0]
	v_pk_mul_f32 v[4:5], v[4:5], v[64:65] op_sel_hi:[1,0]
	v_pk_mul_f32 v[2:3], v[2:3], v[64:65] op_sel_hi:[1,0]
	v_pk_mul_f32 v[0:1], v[0:1], v[64:65] op_sel_hi:[1,0]
	v_cvt_pk_bf16_f32 v118, v132, v133
	v_cvt_pk_bf16_f32 v119, v134, v117
	v_cvt_pk_bf16_f32 v120, v130, v131
	v_cvt_pk_bf16_f32 v121, v136, v137
	v_mul_f32_e32 v126, 0x3fb8aa3b, v126
	v_mul_f32_e32 v122, 0x3fb8aa3b, v122
	s_waitcnt vmcnt(3)
	v_permlane32_swap_b32_e32 v32, v34
	v_permlane32_swap_b32_e32 v33, v35
	s_nop 1
	v_mfma_f32_32x32x16_bf16 v[0:15], v[32:35], v[118:121], v[0:15]
	v_mul_f32_e32 v123, 0x3fb8aa3b, v123
	v_mul_f32_e32 v124, 0x3fb8aa3b, v124
	v_mul_f32_e32 v125, 0x3fb8aa3b, v125
	v_mul_f32_e32 v127, 0x3fb8aa3b, v127
	v_mul_f32_e32 v128, 0x3fb8aa3b, v128
	v_mul_f32_e32 v129, 0x3fb8aa3b, v129
	v_exp_f32_e32 v126, v126
	v_exp_f32_e32 v122, v122
	v_exp_f32_e32 v123, v123
	v_exp_f32_e32 v124, v124
	v_exp_f32_e32 v125, v125
	v_exp_f32_e32 v127, v127
	v_exp_f32_e32 v128, v128
	v_exp_f32_e32 v129, v129
	v_pk_mul_f32 v[30:31], v[30:31], v[64:65] op_sel_hi:[1,0]
	v_pk_mul_f32 v[28:29], v[28:29], v[64:65] op_sel_hi:[1,0]
	v_pk_mul_f32 v[26:27], v[26:27], v[64:65] op_sel_hi:[1,0]
	v_pk_mul_f32 v[24:25], v[24:25], v[64:65] op_sel_hi:[1,0]
	v_pk_mul_f32 v[22:23], v[22:23], v[64:65] op_sel_hi:[1,0]
	v_pk_mul_f32 v[20:21], v[20:21], v[64:65] op_sel_hi:[1,0]
	v_pk_mul_f32 v[18:19], v[18:19], v[64:65] op_sel_hi:[1,0]
	v_pk_mul_f32 v[16:17], v[16:17], v[64:65] op_sel_hi:[1,0]
	s_waitcnt vmcnt(1)
	v_permlane32_swap_b32_e32 v40, v42
	v_permlane32_swap_b32_e32 v41, v43
	s_nop 1
	v_mfma_f32_32x32x16_bf16 v[16:31], v[40:43], v[118:121], v[16:31]
	v_add_f32_e32 v40, 0, v132
	v_add_f32_e32 v40, v133, v40
	v_cvt_pk_bf16_f32 v32, v126, v122
	v_cvt_pk_bf16_f32 v33, v123, v124
	v_cvt_pk_bf16_f32 v34, v125, v127
	v_cvt_pk_bf16_f32 v35, v128, v129
	v_add_f32_e32 v40, v134, v40
	s_movk_i32 s89, 0x2200
	v_permlane32_swap_b32_e32 v36, v38
	v_permlane32_swap_b32_e32 v37, v39
	s_nop 1
	v_mfma_f32_32x32x16_bf16 v[0:15], v[36:39], v[32:35], v[0:15]
	v_add_f32_e32 v36, v117, v40
	v_add_f32_e32 v36, v130, v36
	v_add_f32_e32 v36, v131, v36
	v_add_f32_e32 v36, v136, v36
	v_add_f32_e32 v36, v137, v36
	v_add_f32_e32 v36, v126, v36
	v_add_f32_e32 v36, v122, v36
	s_waitcnt vmcnt(0)
	v_permlane32_swap_b32_e32 v44, v46
	v_permlane32_swap_b32_e32 v45, v47
	s_nop 1
	v_mfma_f32_32x32x16_bf16 v[16:31], v[44:47], v[32:35], v[16:31]
	v_add_f32_e32 v32, v123, v36
	v_add_f32_e32 v32, v124, v32
	v_add_f32_e32 v32, v125, v32
	v_add_f32_e32 v32, v127, v32
	v_add_f32_e32 v32, v128, v32
	v_add_f32_e32 v117, v129, v32
	v_fmac_f32_e32 v117, v135, v64
	s_andn2_b64 exec, exec, s[0:1]
	s_cbranch_execnz .LBB0_248
	s_or_b64 exec, exec, s[0:1]
	v_readlane_b32 s68, v254, 25
	v_readlane_b32 s72, v254, 29
	v_readlane_b32 s73, v254, 30
	v_readlane_b32 s70, v254, 27
	v_readlane_b32 s71, v254, 28
	v_readlane_b32 s82, v254, 39
	v_readlane_b32 s83, v254, 40
	v_readlane_b32 s90, v254, 45
	v_readlane_b32 s86, v254, 47
	v_readlane_b32 s72, v254, 51
	v_readlane_b32 s16, v254, 59
	v_readlane_b32 s20, v254, 53
	v_readlane_b32 s22, v254, 55
	v_readlane_b32 s2, v254, 57
	s_mov_b64 s[70:71], s[82:83]
	v_readlane_b32 s91, v254, 46
	s_mov_b32 s88, s86
	s_mov_b32 s84, s72
	v_readlane_b32 s17, v254, 60
	v_readlane_b32 s21, v254, 54
	v_readlane_b32 s23, v254, 56
	v_readlane_b32 s3, v254, 58
	v_readlane_b32 s69, v254, 26
	v_readlane_b32 s74, v254, 31
	v_readlane_b32 s75, v254, 32
	v_readlane_b32 s76, v254, 33
	v_readlane_b32 s77, v254, 34
	v_readlane_b32 s78, v254, 35
	v_readlane_b32 s79, v254, 36
	v_readlane_b32 s80, v254, 37
	v_readlane_b32 s81, v254, 38
	v_readlane_b32 s87, v254, 48
	v_readlane_b32 s73, v254, 52
	s_branch .LBB0_243
.LBB0_250:
	v_readlane_b32 s0, v254, 43
	v_readlane_b32 s1, v254, 44
	s_or_b64 exec, exec, s[0:1]
	v_mov_b32_e32 v1, v178
	v_readlane_b32 s2, v254, 22
	v_ashrrev_i32_e32 v0, 6, v1
	s_movk_i32 s33, 0x1000
	v_add_u32_e32 v88, s2, v0
	s_mov_b64 s[30:31], 0
	s_mov_b64 s[0:1], 0
	v_cmp_gt_i32_e32 vcc, s33, v88
	s_and_saveexec_b64 s[34:35], vcc
	s_cbranch_execz .LBB0_257
	v_readlane_b32 s2, v254, 0
	v_readlane_b32 s3, v254, 1
	s_add_u32 s36, s2, s0
	v_and_b32_e32 v89, 31, v1
	s_addc_u32 s37, s3, s1
	v_mov_b32_e32 v65, 0
	v_lshlrev_b32_e32 v64, 12, v89
	v_bfe_u32 v1, v1, 5, 1
	v_lshl_add_u64 v[4:5], s[36:37], 0, v[64:65]
	s_mov_b64 s[0:1], 0x14920000
	v_lshl_add_u64 v[66:67], v[4:5], 0, s[0:1]
	v_lshlrev_b32_e32 v4, 2, v1
	s_add_u32 s38, s36, 0xc120000
	v_cmp_eq_u32_e32 vcc, 0, v1
	v_lshlrev_b32_e32 v2, 3, v1
	v_or_b32_e32 v6, 8, v4
	v_or_b32_e32 v8, 16, v4
	v_or_b32_e32 v10, 24, v4
	v_lshlrev_b32_e32 v0, 5, v0
	s_addc_u32 s39, s37, 0
	v_cndmask_b32_e64 v90, 0, 1.0, vcc
	v_mul_i32_i24_e32 v91, -4, v1
	v_lshl_add_u32 v92, s88, 8, v0
	s_lshl_b32 s52, s90, 8
	s_movk_i32 s53, 0x780
	s_movk_i32 s54, 0x60
	s_movk_i32 s55, 0x2200
	s_mov_b64 s[40:41], 0x20000
	s_mov_b64 s[42:43], 0x1000
	s_movk_i32 s56, 0x81
	s_mov_b64 s[44:45], 0x15d20400
	s_mov_b64 s[46:47], 0x15d20440
	v_lshlrev_b32_e32 v68, 1, v4
	v_lshlrev_b32_e32 v70, 1, v6
	v_lshlrev_b32_e32 v72, 1, v8
	v_lshlrev_b32_e32 v74, 1, v10
	s_movk_i32 s57, 0xfff
	v_lshlrev_b32_e32 v76, 1, v2
	v_mov_b32_e32 v93, 0xff800000
	s_branch .LBB0_253

.LBB0_255:
	v_add_u32_e32 v36, v89, v69
	v_mov_b32_e32 v94, v32
	v_lshlrev_b64 v[32:33], 1, v[64:65]
	v_mad_i64_i32 v[36:37], s[0:1], v36, s55, v[82:83]
	v_add_u32_e32 v34, 16, v64
	v_mov_b32_e32 v35, v65
	v_lshl_add_u64 v[38:39], v[84:85], 0, v[32:33]
	v_lshl_add_u64 v[38:39], v[38:39], 0, v[164:165]
	v_lshl_add_u64 v[32:33], v[86:87], 0, v[32:33]
	v_lshl_add_u64 v[32:33], v[32:33], 0, v[164:165]
	v_lshl_add_u64 v[36:37], v[36:37], 0, v[76:77]
	v_lshl_add_u64 v[34:35], v[34:35], 1, v[86:87]
	v_lshl_add_u64 v[34:35], v[34:35], 0, v[164:165]
	global_load_dwordx4 v[96:99], v[38:39], off
	global_load_dwordx4 v[100:103], v[38:39], off offset:32
	global_load_dwordx4 v[104:107], v[32:33], off
	global_load_dwordx4 v[108:111], v[34:35], off
	v_add_co_u32_e64 v32, s[0:1], s33, v36
	v_lshl_add_u64 v[120:121], v[36:37], 0, s[42:43]
	s_nop 0
	v_addc_co_u32_e64 v33, s[0:1], 0, v37, s[0:1]
	global_load_dwordx4 v[32:35], v[32:33], off
	s_nop 0
	global_load_dwordx4 v[112:115], v[120:121], off offset:32
	global_load_dwordx4 v[116:119], v[120:121], off offset:96
	v_add_u32_e32 v40, v89, v75
	v_add_u32_e32 v154, s56, v40
	v_add_u32_e32 v154, -1, v154
	v_lshl_add_u32 v156, s56, 1, -1
	global_load_dwordx4 v[120:123], v[120:121], off offset:64
	s_waitcnt vmcnt(19)
	s_waitcnt vmcnt(18)
	v_subrev_u32_e32 v149, 0, v154
	v_subrev_u32_e32 v150, 1, v154
	v_subrev_u32_e32 v151, 2, v154
	v_add_u32_e32 v71, 1, v71
	v_cmp_ge_u32_e32 vcc, v71, v73
	v_subrev_u32_e32 v95, 3, v154
	s_or_b64 s[50:51], vcc, s[50:51]
	v_cmp_gt_u32_e32 vcc, v156, v150
	v_cmp_gt_u32_e64 s[2:3], v156, v95
	v_cmp_gt_u32_e64 s[28:29], v156, v149
	v_cmp_gt_u32_e64 s[0:1], v156, v151
	v_subrev_u32_e32 v124, 16, v154
	v_cmp_gt_u32_e64 s[12:13], v156, v124
	v_subrev_u32_e32 v75, 32, v75
	v_add_u32_e32 v64, 32, v64
	v_add_u32_e32 v69, 32, v69
	s_waitcnt vmcnt(3)
	v_mfma_f32_32x32x16_bf16 v[32:47], v[32:35], v[48:51], 0
	s_waitcnt vmcnt(2)
	v_mfma_f32_32x32x16_bf16 v[32:47], v[112:115], v[52:55], v[32:47]
	v_subrev_u32_e32 v112, 8, v154
	v_cmp_gt_u32_e64 s[4:5], v156, v112
	v_subrev_u32_e32 v113, 9, v154
	v_subrev_u32_e32 v114, 10, v154
	v_subrev_u32_e32 v115, 11, v154
	v_cmp_gt_u32_e64 s[6:7], v156, v113
	v_cmp_gt_u32_e64 s[8:9], v156, v114
	s_waitcnt vmcnt(0)
	v_mfma_f32_32x32x16_bf16 v[32:47], v[120:123], v[56:59], v[32:47]
	v_subrev_u32_e32 v125, 17, v154
	v_cmp_gt_u32_e64 s[10:11], v156, v115
	v_subrev_u32_e32 v120, 18, v154
	v_subrev_u32_e32 v121, 19, v154
	v_cmp_gt_u32_e64 s[14:15], v156, v125
	v_subrev_u32_e32 v122, 24, v154
	v_subrev_u32_e32 v123, 25, v154
	v_mfma_f32_32x32x16_bf16 v[32:47], v[116:119], v[60:63], v[32:47]
	v_cmp_gt_u32_e64 s[16:17], v156, v120
	v_cmp_gt_u32_e64 s[18:19], v156, v121
	v_subrev_u32_e32 v126, 26, v154
	v_subrev_u32_e32 v127, 27, v154
	v_cmp_gt_u32_e64 s[20:21], v156, v122
	v_cmp_gt_u32_e64 s[22:23], v156, v123
	v_cmp_gt_u32_e64 s[24:25], v156, v126
	s_nop 4
	v_cndmask_b32_e64 v32, v93, v32, s[28:29]
	v_cndmask_b32_e32 v33, v93, v33, vcc
	v_max_f32_e32 v95, 0xf149f2ca, v32
	v_cndmask_b32_e64 v34, v93, v34, s[0:1]
	v_cndmask_b32_e64 v35, v93, v35, s[2:3]
	v_max_f32_e32 v95, v95, v33
	v_cndmask_b32_e64 v36, v93, v36, s[4:5]
	v_cndmask_b32_e64 v37, v93, v37, s[6:7]
	v_max3_f32 v95, v95, v34, v35
	v_cndmask_b32_e64 v38, v93, v38, s[8:9]
	v_cndmask_b32_e64 v39, v93, v39, s[10:11]
	v_max3_f32 v95, v95, v36, v37
	v_cndmask_b32_e64 v40, v93, v40, s[12:13]
	v_cndmask_b32_e64 v41, v93, v41, s[14:15]
	v_max3_f32 v95, v95, v38, v39
	v_cndmask_b32_e64 v42, v93, v42, s[16:17]
	v_cndmask_b32_e64 v43, v93, v43, s[18:19]
	v_max3_f32 v95, v95, v40, v41
	v_cmp_gt_u32_e64 s[26:27], v156, v127
	v_cndmask_b32_e64 v44, v93, v44, s[20:21]
	v_cndmask_b32_e64 v45, v93, v45, s[22:23]
	v_max3_f32 v95, v95, v42, v43
	v_cndmask_b32_e64 v46, v93, v46, s[24:25]
	v_cndmask_b32_e64 v47, v93, v47, s[26:27]
	v_max3_f32 v95, v95, v44, v45
	v_max3_f32 v95, v95, v46, v47
	v_mov_b32_e32 v112, v95
	s_nop 1
	v_permlane32_swap_b32_e32 v95, v112
	v_max3_f32 v95, v81, v95, v112
	v_sub_f32_e32 v32, v32, v95
	v_sub_f32_e32 v33, v33, v95
	v_sub_f32_e32 v34, v34, v95
	v_sub_f32_e32 v35, v35, v95
	v_sub_f32_e32 v36, v36, v95
	v_sub_f32_e32 v37, v37, v95
	v_sub_f32_e32 v38, v38, v95
	v_sub_f32_e32 v39, v39, v95
	v_sub_f32_e32 v112, v81, v95
	v_mul_f32_e32 v32, 0x3fb8aa3b, v32
	v_mul_f32_e32 v33, 0x3fb8aa3b, v33
	v_mul_f32_e32 v34, 0x3fb8aa3b, v34
	v_mul_f32_e32 v35, 0x3fb8aa3b, v35
	v_mul_f32_e32 v36, 0x3fb8aa3b, v36
	v_mul_f32_e32 v37, 0x3fb8aa3b, v37
	v_mul_f32_e32 v38, 0x3fb8aa3b, v38
	v_mul_f32_e32 v39, 0x3fb8aa3b, v39
	v_sub_f32_e32 v40, v40, v95
	v_sub_f32_e32 v41, v41, v95
	v_sub_f32_e32 v42, v42, v95
	v_sub_f32_e32 v43, v43, v95
	v_sub_f32_e32 v44, v44, v95
	v_sub_f32_e32 v45, v45, v95
	v_sub_f32_e32 v46, v46, v95
	v_sub_f32_e32 v47, v47, v95
	v_mov_b32_e32 v81, v95
	v_mul_f32_e32 v95, 0x3fb8aa3b, v112
	v_exp_f32_e32 v32, v32
	v_exp_f32_e32 v113, v33
	v_exp_f32_e32 v114, v34
	v_exp_f32_e32 v115, v35
	v_exp_f32_e32 v112, v36
	v_exp_f32_e32 v37, v37
	v_exp_f32_e32 v38, v38
	v_exp_f32_e32 v39, v39
	v_exp_f32_e32 v36, v95
	v_cndmask_b32_e64 v95, 0, v32, s[28:29]
	v_pk_mul_f32 v[14:15], v[14:15], v[36:37] op_sel_hi:[1,0]
	v_pk_mul_f32 v[12:13], v[12:13], v[36:37] op_sel_hi:[1,0]
	v_pk_mul_f32 v[10:11], v[10:11], v[36:37] op_sel_hi:[1,0]
	v_pk_mul_f32 v[8:9], v[8:9], v[36:37] op_sel_hi:[1,0]
	v_pk_mul_f32 v[6:7], v[6:7], v[36:37] op_sel_hi:[1,0]
	v_pk_mul_f32 v[4:5], v[4:5], v[36:37] op_sel_hi:[1,0]
	v_pk_mul_f32 v[2:3], v[2:3], v[36:37] op_sel_hi:[1,0]
	v_pk_mul_f32 v[0:1], v[0:1], v[36:37] op_sel_hi:[1,0]
	v_pk_mul_f32 v[30:31], v[30:31], v[36:37] op_sel_hi:[1,0]
	v_cvt_pk_bf16_f32 v32, v95, v113
	v_cvt_pk_bf16_f32 v33, v114, v115
	v_cvt_pk_bf16_f32 v34, v112, v37
	v_cvt_pk_bf16_f32 v35, v38, v39
	v_pk_mul_f32 v[28:29], v[28:29], v[36:37] op_sel_hi:[1,0]
	v_pk_mul_f32 v[26:27], v[26:27], v[36:37] op_sel_hi:[1,0]
	v_pk_mul_f32 v[24:25], v[24:25], v[36:37] op_sel_hi:[1,0]
	v_pk_mul_f32 v[22:23], v[22:23], v[36:37] op_sel_hi:[1,0]
	v_pk_mul_f32 v[20:21], v[20:21], v[36:37] op_sel_hi:[1,0]
	v_pk_mul_f32 v[18:19], v[18:19], v[36:37] op_sel_hi:[1,0]
	v_pk_mul_f32 v[16:17], v[16:17], v[36:37] op_sel_hi:[1,0]
	v_add_f32_e32 v95, 0, v95
	v_permlane32_swap_b32_e32 v96, v98
	v_permlane32_swap_b32_e32 v97, v99
	s_nop 1
	v_mfma_f32_32x32x16_bf16 v[0:15], v[96:99], v[32:35], v[0:15]
	v_add_f32_e32 v95, v113, v95
	v_mul_f32_e32 v40, 0x3fb8aa3b, v40
	v_mul_f32_e32 v41, 0x3fb8aa3b, v41
	v_mul_f32_e32 v42, 0x3fb8aa3b, v42
	v_mul_f32_e32 v43, 0x3fb8aa3b, v43
	v_mul_f32_e32 v44, 0x3fb8aa3b, v44
	v_mul_f32_e32 v45, 0x3fb8aa3b, v45
	v_permlane32_swap_b32_e32 v104, v106
	v_permlane32_swap_b32_e32 v105, v107
	s_nop 1
	v_mfma_f32_32x32x16_bf16 v[16:31], v[104:107], v[32:35], v[16:31]
	v_mul_f32_e32 v46, 0x3fb8aa3b, v46
	v_mul_f32_e32 v47, 0x3fb8aa3b, v47
	v_add_f32_e32 v95, v114, v95
	v_exp_f32_e32 v40, v40
	v_exp_f32_e32 v41, v41
	v_exp_f32_e32 v42, v42
	v_exp_f32_e32 v43, v43
	v_exp_f32_e32 v44, v44
	v_exp_f32_e32 v45, v45
	v_exp_f32_e32 v46, v46
	v_exp_f32_e32 v47, v47
	v_add_f32_e32 v95, v115, v95
	v_add_f32_e32 v95, v112, v95
	v_add_f32_e32 v37, v37, v95
	v_add_f32_e32 v37, v38, v37
	v_add_f32_e32 v37, v39, v37
	v_cvt_pk_bf16_f32 v32, v40, v41
	v_cvt_pk_bf16_f32 v33, v42, v43
	v_cvt_pk_bf16_f32 v34, v44, v45
	v_cvt_pk_bf16_f32 v35, v46, v47
	v_add_f32_e32 v37, v40, v37
	v_add_f32_e32 v37, v41, v37
	v_permlane32_swap_b32_e32 v100, v102
	v_permlane32_swap_b32_e32 v101, v103
	s_nop 1
	v_mfma_f32_32x32x16_bf16 v[0:15], v[100:103], v[32:35], v[0:15]
	v_permlane32_swap_b32_e32 v108, v110
	v_permlane32_swap_b32_e32 v109, v111
	s_nop 1
	v_mfma_f32_32x32x16_bf16 v[16:31], v[108:111], v[32:35], v[16:31]
	v_add_f32_e32 v32, v42, v37
	v_add_f32_e32 v32, v43, v32
	v_add_f32_e32 v32, v44, v32
	v_add_f32_e32 v32, v45, v32
	v_add_f32_e32 v32, v46, v32
	v_add_f32_e32 v32, v47, v32
	v_fmac_f32_e32 v32, v94, v36
	s_andn2_b64 exec, exec, s[50:51]
	s_cbranch_execnz .LBB0_255
	s_or_b64 exec, exec, s[50:51]
	s_branch .LBB0_252

.LBB0_826:
	s_or_b64 exec, exec, s[0:1]
	s_waitcnt lgkmcnt(0)
	v_mov_b32_e32 v0, v178
	s_barrier
	v_readlane_b32 s2, v254, 22
	v_ashrrev_i32_e32 v1, 6, v0
	s_mov_b64 s[16:17], 0
	s_mov_b64 s[0:1], 0
	v_add_u32_e32 v69, s2, v1
	s_movk_i32 s2, 0x1000
	v_cmp_gt_i32_e32 vcc, s2, v69
	s_mov_b64 s[2:3], exec
	v_writelane_b32 v255, s2, 6
	s_nop 1
	v_writelane_b32 v255, s3, 7
	s_and_b64 s[2:3], s[2:3], vcc
	s_mov_b64 exec, s[2:3]
	s_cbranch_execz .LBB0_835
	v_readlane_b32 s2, v254, 0
	v_readlane_b32 s3, v254, 1
	s_add_u32 s0, s2, s0
	s_addc_u32 s1, s3, s1
	s_add_u32 s4, s0, 0xc120000
	s_addc_u32 s5, s1, 0
	v_writelane_b32 v254, s4, 55
	s_movk_i32 s85, 0x2200
	v_and_b32_e32 v104, 31, v0
	v_writelane_b32 v254, s5, 56
	v_writelane_b32 v254, s84, 51
	s_add_u32 s18, s0, 0x15d20000
	v_mov_b32_e32 v65, 0
	v_writelane_b32 v254, s85, 52
	v_writelane_b32 v254, s89, 49
	v_lshlrev_b32_e32 v64, 12, v104
	v_writelane_b32 v254, s92, 53
	v_and_b32_e32 v2, 63, v0
	s_addc_u32 s19, s1, 0
	s_movk_i32 s2, 0x780
	v_lshl_add_u64 v[4:5], s[0:1], 0, v[64:65]
	s_mov_b64 s[0:1], 0x14920000
	v_writelane_b32 v254, s93, 54
	v_mul_lo_u32 v105, v1, s2
	v_bfe_u32 v1, v0, 5, 1
	v_lshl_add_u64 v[66:67], v[4:5], 0, s[0:1]
	v_or_b32_e32 v14, 0x180, v2
	s_movk_i32 s0, 0x191
	v_writelane_b32 v254, s18, 41
	v_lshlrev_b32_e32 v68, 2, v1
	v_cmp_gt_u32_e64 s[20:21], s0, v14
	v_writelane_b32 v254, s19, 42
	v_bfe_u32 v106, v0, 4, 1
	v_and_b32_e32 v107, 15, v0
	v_lshlrev_b32_e32 v0, 3, v1
	v_or_b32_e32 v4, 64, v2
	v_or_b32_e32 v6, 0x80, v2
	v_or_b32_e32 v8, 0xc0, v2
	v_or_b32_e32 v10, 0x100, v2
	v_or_b32_e32 v12, 0x140, v2
	v_or_b32_e32 v16, 0x1c0, v2
	v_lshlrev_b32_e32 v64, 4, v1
	v_lshlrev_b32_e32 v90, 1, v68
	v_writelane_b32 v254, s20, 43
	v_lshl_add_u32 v108, v2, 2, v105
	v_lshl_add_u64 v[70:71], s[4:5], 0, v[64:65]
	v_lshlrev_b32_e32 v72, 2, v2
	v_mov_b32_e32 v73, v65
	v_lshlrev_b32_e32 v74, 2, v4
	v_mov_b32_e32 v75, v65
	v_lshlrev_b32_e32 v76, 2, v6
	v_mov_b32_e32 v77, v65
	v_lshlrev_b32_e32 v78, 2, v8
	v_mov_b32_e32 v79, v65
	v_lshlrev_b32_e32 v80, 2, v10
	v_mov_b32_e32 v81, v65
	v_lshlrev_b32_e32 v82, 2, v12
	v_mov_b32_e32 v83, v65
	v_lshlrev_b32_e32 v84, 2, v14
	v_mov_b32_e32 v85, v65
	v_lshlrev_b32_e32 v86, 2, v16
	v_lshlrev_b32_e32 v88, 1, v0
	v_mov_b32_e32 v92, v90
	v_mov_b32_e32 v93, v65
	v_mov_b32_e32 v109, 0xff800000
	v_writelane_b32 v254, s21, 44
	s_branch .LBB0_829

.LBB0_833:
	v_add_u32_e32 v32, s33, v91
	v_lshl_or_b32 v64, v32, 6, v89
	v_sub_u32_e32 v33, v32, v87
	v_cmp_ge_u32_e32 vcc, v32, v111
	v_cmp_lt_u32_e64 s[2:3], v32, v113
	v_add_u32_e32 v32, v112, v64
	v_max_i32_e32 v33, -7, v33
	s_and_b64 s[86:87], vcc, s[2:3]
	v_mad_i64_i32 v[36:37], s[2:3], v32, s85, v[100:101]
	v_add_u32_e32 v38, 7, v33
	global_load_dwordx4 v[32:35], v[36:37], off offset:1024
	global_load_dwordx4 v[132:135], v[36:37], off offset:1056
	global_load_dwordx4 v[136:139], v[36:37], off offset:1088
	global_load_dwordx4 v[140:143], v[36:37], off offset:1120
	v_min_u32_e32 v36, 14, v38
	s_movk_i32 vcc_lo, 0x7c
	v_mad_u32_u24 v131, v36, vcc_lo, v105
	v_lshl_add_u32 v160, v161, 2, v131
	ds_read_b32 v144, v160
	ds_read_b32 v145, v160 offset:4
	v_readlane_b32 s2, v254, 61
	v_readlane_b32 s3, v254, 62
	s_and_b64 s[2:3], s[86:87], s[2:3]
	s_and_b64 s[4:5], s[86:87], s[8:9]
	s_and_b64 s[96:97], s[86:87], s[12:13]
	s_and_b64 s[94:95], s[86:87], s[16:17]
	s_and_b64 s[4:5], s[4:5], s[10:11]
	s_and_b64 s[2:3], s[2:3], s[6:7]
	s_and_b64 s[92:93], s[86:87], s[20:21]
	s_and_b64 s[90:91], s[86:87], s[24:25]
	s_and_b64 s[96:97], s[96:97], s[14:15]
	s_and_b64 s[94:95], s[94:95], s[18:19]
	s_and_b64 s[88:89], s[86:87], s[28:29]
	s_and_b64 s[70:71], s[86:87], s[34:35]
	s_and_b64 s[92:93], s[92:93], s[22:23]
	s_and_b64 s[90:91], s[90:91], s[26:27]
	s_and_b64 s[72:73], s[86:87], s[38:39]
	s_and_b64 s[74:75], s[86:87], s[42:43]
	s_and_b64 s[88:89], s[88:89], s[30:31]
	s_and_b64 s[70:71], s[70:71], s[36:37]
	s_and_b64 s[76:77], s[86:87], s[46:47]
	s_and_b64 s[78:79], s[86:87], s[50:51]
	s_and_b64 s[72:73], s[72:73], s[40:41]
	s_and_b64 s[74:75], s[74:75], s[44:45]
	s_and_b64 s[80:81], s[86:87], s[54:55]
	s_and_b64 s[82:83], s[86:87], s[58:59]
	s_and_b64 s[76:77], s[76:77], s[48:49]
	s_and_b64 s[78:79], s[78:79], s[52:53]
	s_and_b64 s[84:85], s[86:87], s[62:63]
	s_and_b64 s[86:87], s[86:87], s[66:67]
	s_and_b64 s[80:81], s[80:81], s[56:57]
	s_and_b64 s[82:83], s[82:83], s[60:61]
	s_and_b64 s[84:85], s[84:85], s[64:65]
	s_and_b64 s[86:87], s[86:87], s[68:69]
	s_add_i32 s33, s33, 1
	v_cmp_ge_i32_e32 vcc, s33, v110
	s_or_b64 s[0:1], vcc, s[0:1]
	s_waitcnt vmcnt(3)
	v_mfma_f32_32x32x16_bf16 v[32:47], v[32:35], v[48:51], 0
	s_waitcnt vmcnt(2)
	v_mfma_f32_32x32x16_bf16 v[32:47], v[132:135], v[52:55], v[32:47]
	ds_read_b32 v132, v160 offset:8
	ds_read_b32 v133, v160 offset:12
	ds_read_b32 v134, v160 offset:32
	ds_read_b32 v135, v160 offset:36
	ds_read_b32 v146, v160 offset:40
	ds_read_b32 v147, v160 offset:44
	ds_read_b32 v148, v160 offset:64
	s_waitcnt vmcnt(1)
	v_mfma_f32_32x32x16_bf16 v[32:47], v[136:139], v[56:59], v[32:47]
	ds_read_b32 v136, v160 offset:68
	ds_read_b32 v137, v160 offset:72
	ds_read_b32 v138, v160 offset:76
	ds_read_b32 v139, v160 offset:96
	ds_read_b32 v149, v160 offset:100
	ds_read_b32 v150, v160 offset:104
	ds_read_b32 v131, v160 offset:108
	s_waitcnt vmcnt(0)
	v_mfma_f32_32x32x16_bf16 v[32:47], v[140:143], v[60:63], v[32:47]
	s_waitcnt lgkmcnt(14)
	s_nop 10
	v_add_f32_e32 v32, v32, v144
	v_add_f32_e32 v33, v33, v145
	s_waitcnt lgkmcnt(13)
	v_add_f32_e32 v34, v34, v132
	s_waitcnt lgkmcnt(12)
	v_add_f32_e32 v132, v35, v133
	v_cndmask_b32_e64 v32, v109, v32, s[2:3]
	s_waitcnt lgkmcnt(11)
	v_add_f32_e32 v133, v36, v134
	v_cndmask_b32_e64 v33, v109, v33, s[4:5]
	v_max_f32_e32 v35, 0xf149f2ca, v32
	s_waitcnt lgkmcnt(10)
	v_add_f32_e32 v134, v37, v135
	s_waitcnt lgkmcnt(9)
	v_add_f32_e32 v135, v38, v146
	v_cndmask_b32_e64 v34, v109, v34, s[96:97]
	v_cndmask_b32_e64 v132, v109, v132, s[94:95]
	v_max_f32_e32 v35, v35, v33
	s_waitcnt lgkmcnt(8)
	v_add_f32_e32 v140, v39, v147
	s_waitcnt lgkmcnt(7)
	v_add_f32_e32 v141, v40, v148
	v_cndmask_b32_e64 v133, v109, v133, s[92:93]
	v_cndmask_b32_e64 v134, v109, v134, s[90:91]
	v_max3_f32 v35, v35, v34, v132
	s_waitcnt lgkmcnt(6)
	v_add_f32_e32 v136, v41, v136
	s_waitcnt lgkmcnt(5)
	v_add_f32_e32 v137, v42, v137
	v_cndmask_b32_e64 v135, v109, v135, s[88:89]
	v_cndmask_b32_e64 v140, v109, v140, s[70:71]
	v_max3_f32 v35, v35, v133, v134
	s_waitcnt lgkmcnt(4)
	v_add_f32_e32 v138, v43, v138
	s_waitcnt lgkmcnt(3)
	v_add_f32_e32 v139, v44, v139
	v_cndmask_b32_e64 v141, v109, v141, s[72:73]
	v_cndmask_b32_e64 v136, v109, v136, s[74:75]
	v_max3_f32 v35, v35, v135, v140
	s_waitcnt lgkmcnt(2)
	v_add_f32_e32 v142, v45, v149
	s_waitcnt lgkmcnt(1)
	v_add_f32_e32 v143, v46, v150
	v_cndmask_b32_e64 v137, v109, v137, s[76:77]
	v_cndmask_b32_e64 v138, v109, v138, s[78:79]
	v_max3_f32 v35, v35, v141, v136
	s_waitcnt lgkmcnt(0)
	v_add_f32_e32 v131, v47, v131
	v_cndmask_b32_e64 v139, v109, v139, s[80:81]
	v_cndmask_b32_e64 v142, v109, v142, s[82:83]
	v_max3_f32 v35, v35, v137, v138
	v_cndmask_b32_e64 v143, v109, v143, s[84:85]
	v_cndmask_b32_e64 v131, v109, v131, s[86:87]
	v_max3_f32 v35, v35, v139, v142
	v_max3_f32 v35, v35, v143, v131
	v_mov_b32_e32 v36, v35
	s_nop 1
	v_permlane32_swap_b32_e32 v35, v36
	v_max3_f32 v144, v97, v35, v36
	v_sub_f32_e32 v32, v32, v144
	v_mul_f32_e32 v32, 0x3fb8aa3b, v32
	v_exp_f32_e32 v145, v32
	v_mov_b32_e32 v148, v130
	v_sub_f32_e32 v130, v132, v144
	v_sub_f32_e32 v132, v133, v144
	v_sub_f32_e32 v32, v33, v144
	v_mul_f32_e32 v32, 0x3fb8aa3b, v32
	v_exp_f32_e32 v146, v32
	v_sub_f32_e32 v133, v134, v144
	v_sub_f32_e32 v134, v135, v144
	v_sub_f32_e32 v135, v140, v144
	v_sub_f32_e32 v32, v34, v144
	v_mul_f32_e32 v32, 0x3fb8aa3b, v32
	v_exp_f32_e32 v147, v32
	v_sub_f32_e32 v131, v131, v144
	v_mul_f32_e32 v130, 0x3fb8aa3b, v130
	v_mul_f32_e32 v132, 0x3fb8aa3b, v132
	v_lshlrev_b64 v[32:33], 1, v[64:65]
	v_lshl_add_u64 v[38:39], v[102:103], 0, v[32:33]
	v_lshl_add_u64 v[38:39], v[38:39], 0, v[164:165]
	v_lshl_add_u64 v[36:37], v[98:99], 0, v[32:33]
	global_load_dwordx4 v[32:35], v[38:39], off
	v_lshl_add_u64 v[46:47], v[36:37], 0, v[92:93]
	v_lshl_add_u64 v[46:47], v[46:47], 0, v[164:165]
	global_load_dwordx4 v[36:39], v[38:39], off offset:32
	s_nop 0
	s_nop 0
	global_load_dwordx4 v[40:43], v[46:47], off
	global_load_dwordx4 v[44:47], v[46:47], off offset:32
	s_nop 0
	v_sub_f32_e32 v64, v97, v144
	v_mul_f32_e32 v133, 0x3fb8aa3b, v133
	v_mul_f32_e32 v134, 0x3fb8aa3b, v134
	v_mul_f32_e32 v135, 0x3fb8aa3b, v135
	v_mul_f32_e32 v64, 0x3fb8aa3b, v64
	v_mul_f32_e32 v131, 0x3fb8aa3b, v131
	v_exp_f32_e32 v130, v130
	v_exp_f32_e32 v132, v132
	v_exp_f32_e32 v133, v133
	v_exp_f32_e32 v134, v134
	v_exp_f32_e32 v135, v135
	v_exp_f32_e32 v131, v131
	v_exp_f32_e32 v64, v64
	v_sub_f32_e32 v140, v141, v144
	v_sub_f32_e32 v136, v136, v144
	v_sub_f32_e32 v137, v137, v144
	v_sub_f32_e32 v138, v138, v144
	v_sub_f32_e32 v139, v139, v144
	v_sub_f32_e32 v141, v142, v144
	v_sub_f32_e32 v142, v143, v144
	v_mov_b32_e32 v97, v144
	v_cndmask_b32_e64 v143, 0, v130, s[94:95]
	v_cndmask_b32_e64 v144, 0, v132, s[92:93]
	v_cndmask_b32_e64 v149, 0, v133, s[90:91]
	v_cndmask_b32_e64 v150, 0, v131, s[86:87]
	v_pk_mul_f32 v[14:15], v[14:15], v[64:65] op_sel_hi:[1,0]
	v_pk_mul_f32 v[12:13], v[12:13], v[64:65] op_sel_hi:[1,0]
	v_pk_mul_f32 v[10:11], v[10:11], v[64:65] op_sel_hi:[1,0]
	v_pk_mul_f32 v[8:9], v[8:9], v[64:65] op_sel_hi:[1,0]
	v_pk_mul_f32 v[6:7], v[6:7], v[64:65] op_sel_hi:[1,0]
	v_pk_mul_f32 v[4:5], v[4:5], v[64:65] op_sel_hi:[1,0]
	v_pk_mul_f32 v[2:3], v[2:3], v[64:65] op_sel_hi:[1,0]
	v_pk_mul_f32 v[0:1], v[0:1], v[64:65] op_sel_hi:[1,0]
	v_cvt_pk_bf16_f32 v130, v145, v146
	v_cvt_pk_bf16_f32 v131, v147, v143
	v_cvt_pk_bf16_f32 v132, v144, v149
	v_cvt_pk_bf16_f32 v133, v134, v135
	v_mul_f32_e32 v140, 0x3fb8aa3b, v140
	v_mul_f32_e32 v136, 0x3fb8aa3b, v136
	s_waitcnt vmcnt(3)
	v_permlane32_swap_b32_e32 v32, v34
	v_permlane32_swap_b32_e32 v33, v35
	s_nop 1
	v_mfma_f32_32x32x16_bf16 v[0:15], v[32:35], v[130:133], v[0:15]
	v_mul_f32_e32 v137, 0x3fb8aa3b, v137
	v_mul_f32_e32 v138, 0x3fb8aa3b, v138
	v_mul_f32_e32 v139, 0x3fb8aa3b, v139
	v_mul_f32_e32 v141, 0x3fb8aa3b, v141
	v_mul_f32_e32 v142, 0x3fb8aa3b, v142
	v_exp_f32_e32 v140, v140
	v_exp_f32_e32 v136, v136
	v_exp_f32_e32 v137, v137
	v_exp_f32_e32 v138, v138
	v_exp_f32_e32 v139, v139
	v_exp_f32_e32 v141, v141
	v_exp_f32_e32 v142, v142
	v_pk_mul_f32 v[30:31], v[30:31], v[64:65] op_sel_hi:[1,0]
	v_pk_mul_f32 v[28:29], v[28:29], v[64:65] op_sel_hi:[1,0]
	v_pk_mul_f32 v[26:27], v[26:27], v[64:65] op_sel_hi:[1,0]
	v_pk_mul_f32 v[24:25], v[24:25], v[64:65] op_sel_hi:[1,0]
	v_pk_mul_f32 v[22:23], v[22:23], v[64:65] op_sel_hi:[1,0]
	v_pk_mul_f32 v[20:21], v[20:21], v[64:65] op_sel_hi:[1,0]
	v_pk_mul_f32 v[18:19], v[18:19], v[64:65] op_sel_hi:[1,0]
	v_pk_mul_f32 v[16:17], v[16:17], v[64:65] op_sel_hi:[1,0]
	s_waitcnt vmcnt(1)
	v_permlane32_swap_b32_e32 v40, v42
	v_permlane32_swap_b32_e32 v41, v43
	s_nop 1
	v_mfma_f32_32x32x16_bf16 v[16:31], v[40:43], v[130:133], v[16:31]
	v_add_f32_e32 v40, 0, v145
	v_add_f32_e32 v40, v146, v40
	v_cvt_pk_bf16_f32 v32, v140, v136
	v_cvt_pk_bf16_f32 v33, v137, v138
	v_cvt_pk_bf16_f32 v34, v139, v141
	v_cvt_pk_bf16_f32 v35, v142, v150
	v_add_f32_e32 v40, v147, v40
	s_movk_i32 s85, 0x2200
	v_permlane32_swap_b32_e32 v36, v38
	v_permlane32_swap_b32_e32 v37, v39
	s_nop 1
	v_mfma_f32_32x32x16_bf16 v[0:15], v[36:39], v[32:35], v[0:15]
	v_add_f32_e32 v36, v143, v40
	v_add_f32_e32 v36, v144, v36
	v_add_f32_e32 v36, v149, v36
	v_add_f32_e32 v36, v134, v36
	v_add_f32_e32 v36, v135, v36
	v_add_f32_e32 v36, v140, v36
	v_add_f32_e32 v36, v136, v36
	s_waitcnt vmcnt(0)
	v_permlane32_swap_b32_e32 v44, v46
	v_permlane32_swap_b32_e32 v45, v47
	s_nop 1
	v_mfma_f32_32x32x16_bf16 v[16:31], v[44:47], v[32:35], v[16:31]
	v_add_f32_e32 v32, v137, v36
	v_add_f32_e32 v32, v138, v32
	v_add_f32_e32 v32, v139, v32
	v_add_f32_e32 v32, v141, v32
	v_add_f32_e32 v32, v142, v32
	v_add_f32_e32 v130, v150, v32
	v_fmac_f32_e32 v130, v148, v64
	s_andn2_b64 exec, exec, s[0:1]
	s_cbranch_execnz .LBB0_833
	s_or_b64 exec, exec, s[0:1]
	v_readlane_b32 s68, v254, 25
	v_readlane_b32 s72, v254, 29
	v_readlane_b32 s73, v254, 30
	v_readlane_b32 s88, v254, 47
	v_readlane_b32 s70, v254, 27
	v_readlane_b32 s71, v254, 28
	v_readlane_b32 s82, v254, 39
	v_readlane_b32 s83, v254, 40
	v_readlane_b32 s90, v254, 45
	v_readlane_b32 s89, v254, 48
	v_readlane_b32 s72, v254, 51
	v_readlane_b32 s92, v254, 53
	v_readlane_b32 s16, v254, 59
	v_readlane_b32 s18, v254, 41
	v_readlane_b32 s20, v254, 43
	v_readlane_b32 s2, v254, 57
	s_mov_b64 s[70:71], s[82:83]
	v_readlane_b32 s91, v254, 46
	s_mov_b32 s84, s72
	v_readlane_b32 s89, v254, 49
	v_readlane_b32 s93, v254, 54
	v_readlane_b32 s17, v254, 60
	v_readlane_b32 s19, v254, 42
	v_readlane_b32 s21, v254, 44
	v_readlane_b32 s3, v254, 58
	v_readlane_b32 s69, v254, 26
	v_readlane_b32 s74, v254, 31
	v_readlane_b32 s75, v254, 32
	v_readlane_b32 s76, v254, 33
	v_readlane_b32 s77, v254, 34
	v_readlane_b32 s78, v254, 35
	v_readlane_b32 s79, v254, 36
	v_readlane_b32 s80, v254, 37
	v_readlane_b32 s81, v254, 38
	v_readlane_b32 s73, v254, 52
	s_branch .LBB0_828
.LBB0_835:
	v_readlane_b32 s0, v255, 6
	v_readlane_b32 s1, v255, 7
	s_or_b64 exec, exec, s[0:1]
	v_mov_b32_e32 v1, v178
	v_readlane_b32 s2, v254, 22
	v_ashrrev_i32_e32 v0, 6, v1
	s_movk_i32 s33, 0x1000
	v_add_u32_e32 v88, s2, v0
	s_mov_b64 s[30:31], 0
	s_mov_b64 s[0:1], 0
	v_cmp_gt_i32_e32 vcc, s33, v88
	s_and_saveexec_b64 s[34:35], vcc
	s_cbranch_execz .LBB0_842
	v_readlane_b32 s2, v254, 0
	v_readlane_b32 s3, v254, 1
	s_add_u32 s36, s2, s0
	v_and_b32_e32 v89, 31, v1
	s_addc_u32 s37, s3, s1
	v_mov_b32_e32 v65, 0
	v_lshlrev_b32_e32 v64, 12, v89
	v_bfe_u32 v1, v1, 5, 1
	v_lshl_add_u64 v[4:5], s[36:37], 0, v[64:65]
	s_mov_b64 s[0:1], 0x14920000
	v_lshl_add_u64 v[66:67], v[4:5], 0, s[0:1]
	v_lshlrev_b32_e32 v4, 2, v1
	s_add_u32 s38, s36, 0xc120000
	v_cmp_eq_u32_e32 vcc, 0, v1
	v_lshlrev_b32_e32 v2, 3, v1
	v_or_b32_e32 v6, 8, v4
	v_or_b32_e32 v8, 16, v4
	v_or_b32_e32 v10, 24, v4
	v_lshlrev_b32_e32 v0, 5, v0
	s_addc_u32 s39, s37, 0
	v_cndmask_b32_e64 v90, 0, 1.0, vcc
	v_mul_i32_i24_e32 v91, -4, v1
	v_lshl_add_u32 v92, s88, 8, v0
	s_lshl_b32 s52, s90, 8
	s_movk_i32 s53, 0x780
	s_movk_i32 s54, 0x60
	s_movk_i32 s55, 0x2200
	s_mov_b64 s[40:41], 0x20000
	s_mov_b64 s[42:43], 0x1000
	s_movk_i32 s56, 0x81
	s_mov_b64 s[44:45], 0x15d20400
	s_mov_b64 s[46:47], 0x15d20440
	v_lshlrev_b32_e32 v68, 1, v4
	v_lshlrev_b32_e32 v70, 1, v6
	v_lshlrev_b32_e32 v72, 1, v8
	v_lshlrev_b32_e32 v74, 1, v10
	s_movk_i32 s57, 0xfff
	v_lshlrev_b32_e32 v76, 1, v2
	v_mov_b32_e32 v93, 0xff800000
	s_branch .LBB0_838
